# SwiGLU epilogue re-emitted with packed f32 ops and stage-wise interleave (same per-element arithmetic)
# speedup vs baseline: 1.0020x; 1.0020x over previous
.LBB0_103:
	s_waitcnt lgkmcnt(0)
	s_barrier
	v_lshl_or_b32 v148, s12, 7, v151
	v_add_u32_e32 v156, s5, v137
	v_ashrrev_i32_e32 v149, 31, v148
	s_movk_i32 s5, 0x1600
	v_mov_b64_e32 v[230:231], s[94:95]
	v_mad_i64_i32 v[228:229], s[10:11], v156, s5, v[230:231]
	v_lshlrev_b64 v[230:231], 1, v[148:149]
	v_lshl_add_u64 v[228:229], v[228:229], 0, v[230:231]
	ds_read_b32 v212, v154
	ds_read_b32 v214, v154 offset:64
	ds_read_b32 v216, v154 offset:128
	ds_read_b32 v218, v154 offset:192
	ds_read_b32 v220, v154 offset:512
	ds_read_b32 v222, v154 offset:576
	ds_read_b32 v224, v154 offset:640
	ds_read_b32 v226, v154 offset:704
	v_mov_b32_e32 v208, 0xbfb8aa3b
	v_mov_b32_e32 v210, 1.0
	s_waitcnt lgkmcnt(0)
	v_pk_mul_f32 v[156:157], v[128:129], v[212:213] op_sel_hi:[1,0]
	v_pk_mul_f32 v[158:159], v[130:131], v[212:213] op_sel_hi:[1,0]
	v_pk_mul_f32 v[160:161], v[120:121], v[212:213] op_sel_hi:[1,0]
	v_pk_mul_f32 v[162:163], v[122:123], v[212:213] op_sel_hi:[1,0]
	v_pk_mul_f32 v[164:165], v[124:125], v[212:213] op_sel_hi:[1,0]
	v_pk_mul_f32 v[166:167], v[126:127], v[212:213] op_sel_hi:[1,0]
	v_pk_mul_f32 v[168:169], v[116:117], v[212:213] op_sel_hi:[1,0]
	v_pk_mul_f32 v[170:171], v[118:119], v[212:213] op_sel_hi:[1,0]
	v_pk_mul_f32 v[172:173], v[156:157], v[208:209] op_sel_hi:[1,0]
	v_pk_mul_f32 v[174:175], v[158:159], v[208:209] op_sel_hi:[1,0]
	v_pk_mul_f32 v[176:177], v[160:161], v[208:209] op_sel_hi:[1,0]
	v_pk_mul_f32 v[178:179], v[162:163], v[208:209] op_sel_hi:[1,0]
	v_exp_f32_e32 v172, v172
	v_exp_f32_e32 v173, v173
	v_exp_f32_e32 v174, v174
	v_exp_f32_e32 v175, v175
	v_exp_f32_e32 v176, v176
	v_exp_f32_e32 v177, v177
	v_exp_f32_e32 v178, v178
	v_exp_f32_e32 v179, v179
	v_pk_add_f32 v[172:173], v[172:173], v[210:211] op_sel_hi:[1,0]
	v_pk_add_f32 v[174:175], v[174:175], v[210:211] op_sel_hi:[1,0]
	v_pk_add_f32 v[176:177], v[176:177], v[210:211] op_sel_hi:[1,0]
	v_pk_add_f32 v[178:179], v[178:179], v[210:211] op_sel_hi:[1,0]
	v_rcp_f32_e32 v172, v172
	v_rcp_f32_e32 v173, v173
	v_rcp_f32_e32 v174, v174
	v_rcp_f32_e32 v175, v175
	v_rcp_f32_e32 v176, v176
	v_rcp_f32_e32 v177, v177
	v_rcp_f32_e32 v178, v178
	v_rcp_f32_e32 v179, v179
	v_pk_mul_f32 v[156:157], v[156:157], v[172:173]
	v_pk_mul_f32 v[158:159], v[158:159], v[174:175]
	v_pk_mul_f32 v[160:161], v[160:161], v[176:177]
	v_pk_mul_f32 v[162:163], v[162:163], v[178:179]
	v_pk_mul_f32 v[156:157], v[164:165], v[156:157]
	v_pk_mul_f32 v[158:159], v[166:167], v[158:159]
	v_pk_mul_f32 v[160:161], v[168:169], v[160:161]
	v_pk_mul_f32 v[162:163], v[170:171], v[162:163]
	v_cvt_pk_bf16_f32 v180, v156, v157
	v_cvt_pk_bf16_f32 v181, v158, v159
	v_cvt_pk_bf16_f32 v182, v160, v161
	v_cvt_pk_bf16_f32 v183, v162, v163
	global_store_dwordx4 v[228:229], v[180:183], off
	v_pk_mul_f32 v[156:157], v[112:113], v[214:215] op_sel_hi:[1,0]
	v_pk_mul_f32 v[158:159], v[114:115], v[214:215] op_sel_hi:[1,0]
	v_pk_mul_f32 v[160:161], v[104:105], v[214:215] op_sel_hi:[1,0]
	v_pk_mul_f32 v[162:163], v[106:107], v[214:215] op_sel_hi:[1,0]
	v_pk_mul_f32 v[164:165], v[108:109], v[214:215] op_sel_hi:[1,0]
	v_pk_mul_f32 v[166:167], v[110:111], v[214:215] op_sel_hi:[1,0]
	v_pk_mul_f32 v[168:169], v[100:101], v[214:215] op_sel_hi:[1,0]
	v_pk_mul_f32 v[170:171], v[102:103], v[214:215] op_sel_hi:[1,0]
	v_pk_mul_f32 v[172:173], v[156:157], v[208:209] op_sel_hi:[1,0]
	v_pk_mul_f32 v[174:175], v[158:159], v[208:209] op_sel_hi:[1,0]
	v_pk_mul_f32 v[176:177], v[160:161], v[208:209] op_sel_hi:[1,0]
	v_pk_mul_f32 v[178:179], v[162:163], v[208:209] op_sel_hi:[1,0]
	v_exp_f32_e32 v172, v172
	v_exp_f32_e32 v173, v173
	v_exp_f32_e32 v174, v174
	v_exp_f32_e32 v175, v175
	v_exp_f32_e32 v176, v176
	v_exp_f32_e32 v177, v177
	v_exp_f32_e32 v178, v178
	v_exp_f32_e32 v179, v179
	v_pk_add_f32 v[172:173], v[172:173], v[210:211] op_sel_hi:[1,0]
	v_pk_add_f32 v[174:175], v[174:175], v[210:211] op_sel_hi:[1,0]
	v_pk_add_f32 v[176:177], v[176:177], v[210:211] op_sel_hi:[1,0]
	v_pk_add_f32 v[178:179], v[178:179], v[210:211] op_sel_hi:[1,0]
	v_rcp_f32_e32 v172, v172
	v_rcp_f32_e32 v173, v173
	v_rcp_f32_e32 v174, v174
	v_rcp_f32_e32 v175, v175
	v_rcp_f32_e32 v176, v176
	v_rcp_f32_e32 v177, v177
	v_rcp_f32_e32 v178, v178
	v_rcp_f32_e32 v179, v179
	v_pk_mul_f32 v[156:157], v[156:157], v[172:173]
	v_pk_mul_f32 v[158:159], v[158:159], v[174:175]
	v_pk_mul_f32 v[160:161], v[160:161], v[176:177]
	v_pk_mul_f32 v[162:163], v[162:163], v[178:179]
	v_pk_mul_f32 v[156:157], v[164:165], v[156:157]
	v_pk_mul_f32 v[158:159], v[166:167], v[158:159]
	v_pk_mul_f32 v[160:161], v[168:169], v[160:161]
	v_pk_mul_f32 v[162:163], v[170:171], v[162:163]
	v_cvt_pk_bf16_f32 v184, v156, v157
	v_cvt_pk_bf16_f32 v185, v158, v159
	v_cvt_pk_bf16_f32 v186, v160, v161
	v_cvt_pk_bf16_f32 v187, v162, v163
	v_add_co_u32_e32 v230, vcc, 0x16000, v228
	s_nop 1
	v_addc_co_u32_e32 v231, vcc, 0, v229, vcc
	global_store_dwordx4 v[230:231], v[184:187], off
	v_pk_mul_f32 v[156:157], v[96:97], v[216:217] op_sel_hi:[1,0]
	v_pk_mul_f32 v[158:159], v[98:99], v[216:217] op_sel_hi:[1,0]
	v_pk_mul_f32 v[160:161], v[88:89], v[216:217] op_sel_hi:[1,0]
	v_pk_mul_f32 v[162:163], v[90:91], v[216:217] op_sel_hi:[1,0]
	v_pk_mul_f32 v[164:165], v[92:93], v[216:217] op_sel_hi:[1,0]
	v_pk_mul_f32 v[166:167], v[94:95], v[216:217] op_sel_hi:[1,0]
	v_pk_mul_f32 v[168:169], v[84:85], v[216:217] op_sel_hi:[1,0]
	v_pk_mul_f32 v[170:171], v[86:87], v[216:217] op_sel_hi:[1,0]
	v_pk_mul_f32 v[172:173], v[156:157], v[208:209] op_sel_hi:[1,0]
	v_pk_mul_f32 v[174:175], v[158:159], v[208:209] op_sel_hi:[1,0]
	v_pk_mul_f32 v[176:177], v[160:161], v[208:209] op_sel_hi:[1,0]
	v_pk_mul_f32 v[178:179], v[162:163], v[208:209] op_sel_hi:[1,0]
	v_exp_f32_e32 v172, v172
	v_exp_f32_e32 v173, v173
	v_exp_f32_e32 v174, v174
	v_exp_f32_e32 v175, v175
	v_exp_f32_e32 v176, v176
	v_exp_f32_e32 v177, v177
	v_exp_f32_e32 v178, v178
	v_exp_f32_e32 v179, v179
	v_pk_add_f32 v[172:173], v[172:173], v[210:211] op_sel_hi:[1,0]
	v_pk_add_f32 v[174:175], v[174:175], v[210:211] op_sel_hi:[1,0]
	v_pk_add_f32 v[176:177], v[176:177], v[210:211] op_sel_hi:[1,0]
	v_pk_add_f32 v[178:179], v[178:179], v[210:211] op_sel_hi:[1,0]
	v_rcp_f32_e32 v172, v172
	v_rcp_f32_e32 v173, v173
	v_rcp_f32_e32 v174, v174
	v_rcp_f32_e32 v175, v175
	v_rcp_f32_e32 v176, v176
	v_rcp_f32_e32 v177, v177
	v_rcp_f32_e32 v178, v178
	v_rcp_f32_e32 v179, v179
	v_pk_mul_f32 v[156:157], v[156:157], v[172:173]
	v_pk_mul_f32 v[158:159], v[158:159], v[174:175]
	v_pk_mul_f32 v[160:161], v[160:161], v[176:177]
	v_pk_mul_f32 v[162:163], v[162:163], v[178:179]
	v_pk_mul_f32 v[156:157], v[164:165], v[156:157]
	v_pk_mul_f32 v[158:159], v[166:167], v[158:159]
	v_pk_mul_f32 v[160:161], v[168:169], v[160:161]
	v_pk_mul_f32 v[162:163], v[170:171], v[162:163]
	v_cvt_pk_bf16_f32 v180, v156, v157
	v_cvt_pk_bf16_f32 v181, v158, v159
	v_cvt_pk_bf16_f32 v182, v160, v161
	v_cvt_pk_bf16_f32 v183, v162, v163
	v_add_co_u32_e32 v230, vcc, 0x2c000, v228
	s_nop 1
	v_addc_co_u32_e32 v231, vcc, 0, v229, vcc
	global_store_dwordx4 v[230:231], v[180:183], off
	v_pk_mul_f32 v[156:157], v[80:81], v[218:219] op_sel_hi:[1,0]
	v_pk_mul_f32 v[158:159], v[82:83], v[218:219] op_sel_hi:[1,0]
	v_pk_mul_f32 v[160:161], v[72:73], v[218:219] op_sel_hi:[1,0]
	v_pk_mul_f32 v[162:163], v[74:75], v[218:219] op_sel_hi:[1,0]
	v_pk_mul_f32 v[164:165], v[76:77], v[218:219] op_sel_hi:[1,0]
	v_pk_mul_f32 v[166:167], v[78:79], v[218:219] op_sel_hi:[1,0]
	v_pk_mul_f32 v[168:169], v[68:69], v[218:219] op_sel_hi:[1,0]
	v_pk_mul_f32 v[170:171], v[70:71], v[218:219] op_sel_hi:[1,0]
	v_pk_mul_f32 v[172:173], v[156:157], v[208:209] op_sel_hi:[1,0]
	v_pk_mul_f32 v[174:175], v[158:159], v[208:209] op_sel_hi:[1,0]
	v_pk_mul_f32 v[176:177], v[160:161], v[208:209] op_sel_hi:[1,0]
	v_pk_mul_f32 v[178:179], v[162:163], v[208:209] op_sel_hi:[1,0]
	v_exp_f32_e32 v172, v172
	v_exp_f32_e32 v173, v173
	v_exp_f32_e32 v174, v174
	v_exp_f32_e32 v175, v175
	v_exp_f32_e32 v176, v176
	v_exp_f32_e32 v177, v177
	v_exp_f32_e32 v178, v178
	v_exp_f32_e32 v179, v179
	v_pk_add_f32 v[172:173], v[172:173], v[210:211] op_sel_hi:[1,0]
	v_pk_add_f32 v[174:175], v[174:175], v[210:211] op_sel_hi:[1,0]
	v_pk_add_f32 v[176:177], v[176:177], v[210:211] op_sel_hi:[1,0]
	v_pk_add_f32 v[178:179], v[178:179], v[210:211] op_sel_hi:[1,0]
	v_rcp_f32_e32 v172, v172
	v_rcp_f32_e32 v173, v173
	v_rcp_f32_e32 v174, v174
	v_rcp_f32_e32 v175, v175
	v_rcp_f32_e32 v176, v176
	v_rcp_f32_e32 v177, v177
	v_rcp_f32_e32 v178, v178
	v_rcp_f32_e32 v179, v179
	v_pk_mul_f32 v[156:157], v[156:157], v[172:173]
	v_pk_mul_f32 v[158:159], v[158:159], v[174:175]
	v_pk_mul_f32 v[160:161], v[160:161], v[176:177]
	v_pk_mul_f32 v[162:163], v[162:163], v[178:179]
	v_pk_mul_f32 v[156:157], v[164:165], v[156:157]
	v_pk_mul_f32 v[158:159], v[166:167], v[158:159]
	v_pk_mul_f32 v[160:161], v[168:169], v[160:161]
	v_pk_mul_f32 v[162:163], v[170:171], v[162:163]
	v_cvt_pk_bf16_f32 v184, v156, v157
	v_cvt_pk_bf16_f32 v185, v158, v159
	v_cvt_pk_bf16_f32 v186, v160, v161
	v_cvt_pk_bf16_f32 v187, v162, v163
	v_add_co_u32_e32 v230, vcc, 0x42000, v228
	s_nop 1
	v_addc_co_u32_e32 v231, vcc, 0, v229, vcc
	global_store_dwordx4 v[230:231], v[184:187], off
	v_pk_mul_f32 v[156:157], v[64:65], v[220:221] op_sel_hi:[1,0]
	v_pk_mul_f32 v[158:159], v[66:67], v[220:221] op_sel_hi:[1,0]
	v_pk_mul_f32 v[160:161], v[56:57], v[220:221] op_sel_hi:[1,0]
	v_pk_mul_f32 v[162:163], v[58:59], v[220:221] op_sel_hi:[1,0]
	v_pk_mul_f32 v[164:165], v[60:61], v[220:221] op_sel_hi:[1,0]
	v_pk_mul_f32 v[166:167], v[62:63], v[220:221] op_sel_hi:[1,0]
	v_pk_mul_f32 v[168:169], v[52:53], v[220:221] op_sel_hi:[1,0]
	v_pk_mul_f32 v[170:171], v[54:55], v[220:221] op_sel_hi:[1,0]
	v_pk_mul_f32 v[172:173], v[156:157], v[208:209] op_sel_hi:[1,0]
	v_pk_mul_f32 v[174:175], v[158:159], v[208:209] op_sel_hi:[1,0]
	v_pk_mul_f32 v[176:177], v[160:161], v[208:209] op_sel_hi:[1,0]
	v_pk_mul_f32 v[178:179], v[162:163], v[208:209] op_sel_hi:[1,0]
	v_exp_f32_e32 v172, v172
	v_exp_f32_e32 v173, v173
	v_exp_f32_e32 v174, v174
	v_exp_f32_e32 v175, v175
	v_exp_f32_e32 v176, v176
	v_exp_f32_e32 v177, v177
	v_exp_f32_e32 v178, v178
	v_exp_f32_e32 v179, v179
	v_pk_add_f32 v[172:173], v[172:173], v[210:211] op_sel_hi:[1,0]
	v_pk_add_f32 v[174:175], v[174:175], v[210:211] op_sel_hi:[1,0]
	v_pk_add_f32 v[176:177], v[176:177], v[210:211] op_sel_hi:[1,0]
	v_pk_add_f32 v[178:179], v[178:179], v[210:211] op_sel_hi:[1,0]
	v_rcp_f32_e32 v172, v172
	v_rcp_f32_e32 v173, v173
	v_rcp_f32_e32 v174, v174
	v_rcp_f32_e32 v175, v175
	v_rcp_f32_e32 v176, v176
	v_rcp_f32_e32 v177, v177
	v_rcp_f32_e32 v178, v178
	v_rcp_f32_e32 v179, v179
	v_pk_mul_f32 v[156:157], v[156:157], v[172:173]
	v_pk_mul_f32 v[158:159], v[158:159], v[174:175]
	v_pk_mul_f32 v[160:161], v[160:161], v[176:177]
	v_pk_mul_f32 v[162:163], v[162:163], v[178:179]
	v_pk_mul_f32 v[156:157], v[164:165], v[156:157]
	v_pk_mul_f32 v[158:159], v[166:167], v[158:159]
	v_pk_mul_f32 v[160:161], v[168:169], v[160:161]
	v_pk_mul_f32 v[162:163], v[170:171], v[162:163]
	v_cvt_pk_bf16_f32 v180, v156, v157
	v_cvt_pk_bf16_f32 v181, v158, v159
	v_cvt_pk_bf16_f32 v182, v160, v161
	v_cvt_pk_bf16_f32 v183, v162, v163
	v_add_co_u32_e32 v230, vcc, 0xb0000, v228
	s_nop 1
	v_addc_co_u32_e32 v231, vcc, 0, v229, vcc
	global_store_dwordx4 v[230:231], v[180:183], off
	v_pk_mul_f32 v[156:157], v[48:49], v[222:223] op_sel_hi:[1,0]
	v_pk_mul_f32 v[158:159], v[50:51], v[222:223] op_sel_hi:[1,0]
	v_pk_mul_f32 v[160:161], v[40:41], v[222:223] op_sel_hi:[1,0]
	v_pk_mul_f32 v[162:163], v[42:43], v[222:223] op_sel_hi:[1,0]
	v_pk_mul_f32 v[164:165], v[44:45], v[222:223] op_sel_hi:[1,0]
	v_pk_mul_f32 v[166:167], v[46:47], v[222:223] op_sel_hi:[1,0]
	v_pk_mul_f32 v[168:169], v[36:37], v[222:223] op_sel_hi:[1,0]
	v_pk_mul_f32 v[170:171], v[38:39], v[222:223] op_sel_hi:[1,0]
	v_pk_mul_f32 v[172:173], v[156:157], v[208:209] op_sel_hi:[1,0]
	v_pk_mul_f32 v[174:175], v[158:159], v[208:209] op_sel_hi:[1,0]
	v_pk_mul_f32 v[176:177], v[160:161], v[208:209] op_sel_hi:[1,0]
	v_pk_mul_f32 v[178:179], v[162:163], v[208:209] op_sel_hi:[1,0]
	v_exp_f32_e32 v172, v172
	v_exp_f32_e32 v173, v173
	v_exp_f32_e32 v174, v174
	v_exp_f32_e32 v175, v175
	v_exp_f32_e32 v176, v176
	v_exp_f32_e32 v177, v177
	v_exp_f32_e32 v178, v178
	v_exp_f32_e32 v179, v179
	v_pk_add_f32 v[172:173], v[172:173], v[210:211] op_sel_hi:[1,0]
	v_pk_add_f32 v[174:175], v[174:175], v[210:211] op_sel_hi:[1,0]
	v_pk_add_f32 v[176:177], v[176:177], v[210:211] op_sel_hi:[1,0]
	v_pk_add_f32 v[178:179], v[178:179], v[210:211] op_sel_hi:[1,0]
	v_rcp_f32_e32 v172, v172
	v_rcp_f32_e32 v173, v173
	v_rcp_f32_e32 v174, v174
	v_rcp_f32_e32 v175, v175
	v_rcp_f32_e32 v176, v176
	v_rcp_f32_e32 v177, v177
	v_rcp_f32_e32 v178, v178
	v_rcp_f32_e32 v179, v179
	v_pk_mul_f32 v[156:157], v[156:157], v[172:173]
	v_pk_mul_f32 v[158:159], v[158:159], v[174:175]
	v_pk_mul_f32 v[160:161], v[160:161], v[176:177]
	v_pk_mul_f32 v[162:163], v[162:163], v[178:179]
	v_pk_mul_f32 v[156:157], v[164:165], v[156:157]
	v_pk_mul_f32 v[158:159], v[166:167], v[158:159]
	v_pk_mul_f32 v[160:161], v[168:169], v[160:161]
	v_pk_mul_f32 v[162:163], v[170:171], v[162:163]
	v_cvt_pk_bf16_f32 v184, v156, v157
	v_cvt_pk_bf16_f32 v185, v158, v159
	v_cvt_pk_bf16_f32 v186, v160, v161
	v_cvt_pk_bf16_f32 v187, v162, v163
	v_add_co_u32_e32 v230, vcc, 0xc6000, v228
	s_nop 1
	v_addc_co_u32_e32 v231, vcc, 0, v229, vcc
	global_store_dwordx4 v[230:231], v[184:187], off
	v_pk_mul_f32 v[156:157], v[32:33], v[224:225] op_sel_hi:[1,0]
	v_pk_mul_f32 v[158:159], v[34:35], v[224:225] op_sel_hi:[1,0]
	v_pk_mul_f32 v[160:161], v[24:25], v[224:225] op_sel_hi:[1,0]
	v_pk_mul_f32 v[162:163], v[26:27], v[224:225] op_sel_hi:[1,0]
	v_pk_mul_f32 v[164:165], v[28:29], v[224:225] op_sel_hi:[1,0]
	v_pk_mul_f32 v[166:167], v[30:31], v[224:225] op_sel_hi:[1,0]
	v_pk_mul_f32 v[168:169], v[20:21], v[224:225] op_sel_hi:[1,0]
	v_pk_mul_f32 v[170:171], v[22:23], v[224:225] op_sel_hi:[1,0]
	v_pk_mul_f32 v[172:173], v[156:157], v[208:209] op_sel_hi:[1,0]
	v_pk_mul_f32 v[174:175], v[158:159], v[208:209] op_sel_hi:[1,0]
	v_pk_mul_f32 v[176:177], v[160:161], v[208:209] op_sel_hi:[1,0]
	v_pk_mul_f32 v[178:179], v[162:163], v[208:209] op_sel_hi:[1,0]
	v_exp_f32_e32 v172, v172
	v_exp_f32_e32 v173, v173
	v_exp_f32_e32 v174, v174
	v_exp_f32_e32 v175, v175
	v_exp_f32_e32 v176, v176
	v_exp_f32_e32 v177, v177
	v_exp_f32_e32 v178, v178
	v_exp_f32_e32 v179, v179
	v_pk_add_f32 v[172:173], v[172:173], v[210:211] op_sel_hi:[1,0]
	v_pk_add_f32 v[174:175], v[174:175], v[210:211] op_sel_hi:[1,0]
	v_pk_add_f32 v[176:177], v[176:177], v[210:211] op_sel_hi:[1,0]
	v_pk_add_f32 v[178:179], v[178:179], v[210:211] op_sel_hi:[1,0]
	v_rcp_f32_e32 v172, v172
	v_rcp_f32_e32 v173, v173
	v_rcp_f32_e32 v174, v174
	v_rcp_f32_e32 v175, v175
	v_rcp_f32_e32 v176, v176
	v_rcp_f32_e32 v177, v177
	v_rcp_f32_e32 v178, v178
	v_rcp_f32_e32 v179, v179
	v_pk_mul_f32 v[156:157], v[156:157], v[172:173]
	v_pk_mul_f32 v[158:159], v[158:159], v[174:175]
	v_pk_mul_f32 v[160:161], v[160:161], v[176:177]
	v_pk_mul_f32 v[162:163], v[162:163], v[178:179]
	v_pk_mul_f32 v[156:157], v[164:165], v[156:157]
	v_pk_mul_f32 v[158:159], v[166:167], v[158:159]
	v_pk_mul_f32 v[160:161], v[168:169], v[160:161]
	v_pk_mul_f32 v[162:163], v[170:171], v[162:163]
	v_cvt_pk_bf16_f32 v180, v156, v157
	v_cvt_pk_bf16_f32 v181, v158, v159
	v_cvt_pk_bf16_f32 v182, v160, v161
	v_cvt_pk_bf16_f32 v183, v162, v163
	v_add_co_u32_e32 v230, vcc, 0xdc000, v228
	s_nop 1
	v_addc_co_u32_e32 v231, vcc, 0, v229, vcc
	global_store_dwordx4 v[230:231], v[180:183], off
	v_pk_mul_f32 v[156:157], v[16:17], v[226:227] op_sel_hi:[1,0]
	v_pk_mul_f32 v[158:159], v[18:19], v[226:227] op_sel_hi:[1,0]
	v_pk_mul_f32 v[160:161], v[8:9], v[226:227] op_sel_hi:[1,0]
	v_pk_mul_f32 v[162:163], v[10:11], v[226:227] op_sel_hi:[1,0]
	v_pk_mul_f32 v[164:165], v[12:13], v[226:227] op_sel_hi:[1,0]
	v_pk_mul_f32 v[166:167], v[14:15], v[226:227] op_sel_hi:[1,0]
	v_pk_mul_f32 v[168:169], v[4:5], v[226:227] op_sel_hi:[1,0]
	v_pk_mul_f32 v[170:171], v[6:7], v[226:227] op_sel_hi:[1,0]
	v_pk_mul_f32 v[172:173], v[156:157], v[208:209] op_sel_hi:[1,0]
	v_pk_mul_f32 v[174:175], v[158:159], v[208:209] op_sel_hi:[1,0]
	v_pk_mul_f32 v[176:177], v[160:161], v[208:209] op_sel_hi:[1,0]
	v_pk_mul_f32 v[178:179], v[162:163], v[208:209] op_sel_hi:[1,0]
	v_exp_f32_e32 v172, v172
	v_exp_f32_e32 v173, v173
	v_exp_f32_e32 v174, v174
	v_exp_f32_e32 v175, v175
	v_exp_f32_e32 v176, v176
	v_exp_f32_e32 v177, v177
	v_exp_f32_e32 v178, v178
	v_exp_f32_e32 v179, v179
	v_pk_add_f32 v[172:173], v[172:173], v[210:211] op_sel_hi:[1,0]
	v_pk_add_f32 v[174:175], v[174:175], v[210:211] op_sel_hi:[1,0]
	v_pk_add_f32 v[176:177], v[176:177], v[210:211] op_sel_hi:[1,0]
	v_pk_add_f32 v[178:179], v[178:179], v[210:211] op_sel_hi:[1,0]
	v_rcp_f32_e32 v172, v172
	v_rcp_f32_e32 v173, v173
	v_rcp_f32_e32 v174, v174
	v_rcp_f32_e32 v175, v175
	v_rcp_f32_e32 v176, v176
	v_rcp_f32_e32 v177, v177
	v_rcp_f32_e32 v178, v178
	v_rcp_f32_e32 v179, v179
	v_pk_mul_f32 v[156:157], v[156:157], v[172:173]
	v_pk_mul_f32 v[158:159], v[158:159], v[174:175]
	v_pk_mul_f32 v[160:161], v[160:161], v[176:177]
	v_pk_mul_f32 v[162:163], v[162:163], v[178:179]
	v_pk_mul_f32 v[156:157], v[164:165], v[156:157]
	v_pk_mul_f32 v[158:159], v[166:167], v[158:159]
	v_pk_mul_f32 v[160:161], v[168:169], v[160:161]
	v_pk_mul_f32 v[162:163], v[170:171], v[162:163]
	v_cvt_pk_bf16_f32 v184, v156, v157
	v_cvt_pk_bf16_f32 v185, v158, v159
	v_cvt_pk_bf16_f32 v186, v160, v161
	v_cvt_pk_bf16_f32 v187, v162, v163
	v_add_co_u32_e32 v230, vcc, 0xf2000, v228
	s_nop 1
	v_addc_co_u32_e32 v231, vcc, 0, v229, vcc
	global_store_dwordx4 v[230:231], v[184:187], off
	s_andn2_b64 vcc, exec, s[38:39]
	s_mov_b64 s[10:11], -1
	s_cbranch_vccnz .LBB0_90
	s_andn2_b64 vcc, exec, s[0:1]
	s_cbranch_vccnz .LBB0_89
	s_barrier
	s_branch .LBB0_89
